# v1 GEMM loops + s_setprio 3 during latent DeltaNet scans
# baseline (speedup 1.0000x reference)
.LBB0_315:
	s_andn2_b64 vcc, exec, s[36:37]
	s_cbranch_vccnz .LBB0_332
	s_setprio 3
	v_readlane_b32 s0, v253, 4
	v_mov_b32_e32 v44, v168
	s_add_i32 s2, s57, s0
	s_bfe_u32 s45, s2, 0x30001
	v_readfirstlane_b32 s3, v44
	s_ashr_i32 s44, s3, 6
	s_ashr_i32 s3, s2, 4
	s_lshl_b32 s66, s3, 5
	s_and_b32 s82, s57, 1
	s_bfe_i32 s2, s57, 0x10000
	s_add_i32 s66, s66, 64
	s_cmp_eq_u32 s82, 0
	s_cselect_b64 s[36:37], -1, 0
	v_readlane_b32 s4, v250, 1
	s_and_b64 s[20:21], s[36:37], exec
	v_readlane_b32 s16, v250, 13
	v_readlane_b32 s17, v250, 14
	v_readlane_b32 s18, v250, 15
	v_readlane_b32 s19, v250, 16
	s_cselect_b32 s38, s17, s19
	s_cselect_b32 s39, s16, s18
	s_lshl_b32 s3, s3, 1
	v_readlane_b32 s0, v254, 61
	s_add_i32 s20, s3, s0
	v_ashrrev_i32_e32 v54, 3, v44
	s_ashr_i32 s21, s20, 31
	v_and_b32_e32 v3, 15, v44
	s_waitcnt vmcnt(0)
	v_sub_u32_e32 v0, 63, v54
	s_lshl_b64 s[20:21], s[20:21], 17
	v_bfe_u32 v52, v44, 4, 2
	v_cndmask_b32_e64 v46, v0, v54, s[36:37]
	s_add_u32 s3, s39, s20
	v_lshl_or_b32 v0, s44, 4, v3
	s_addc_u32 s21, s38, s21
	s_lshl_b32 s20, s45, 14
	v_lshl_add_u32 v0, v52, 8, v0
	s_add_u32 s20, s3, s20
	v_add_u32_e32 v6, 0x400, v0
	v_add_u32_e32 v8, 0x440, v0
	v_add_u32_e32 v10, 0x480, v0
	v_add_u32_e32 v12, 0x4c0, v0
	s_addc_u32 s21, s21, 0
	v_ashrrev_i32_e32 v1, 31, v0
	v_ashrrev_i32_e32 v7, 31, v6
	v_ashrrev_i32_e32 v9, 31, v8
	v_ashrrev_i32_e32 v11, 31, v10
	v_ashrrev_i32_e32 v13, 31, v12
	v_lshl_add_u64 v[4:5], v[0:1], 2, s[20:21]
	v_lshl_add_u64 v[6:7], v[6:7], 2, s[20:21]
	v_lshl_add_u64 v[8:9], v[8:9], 2, s[20:21]
	v_lshl_add_u64 v[10:11], v[10:11], 2, s[20:21]
	v_lshl_add_u64 v[12:13], v[12:13], 2, s[20:21]
	global_load_dword v24, v[4:5], off
	global_load_dword v25, v[4:5], off offset:256
	global_load_dword v26, v[4:5], off offset:512
	global_load_dword v27, v[4:5], off offset:768
	s_nop 0
	global_load_dword v4, v[6:7], off
	global_load_dword v5, v[8:9], off
	s_nop 0
	global_load_dword v6, v[10:11], off
	global_load_dword v7, v[12:13], off
	v_add_u32_e32 v8, 0x800, v0
	v_add_u32_e32 v10, 0x840, v0
	v_add_u32_e32 v12, 0x880, v0
	v_add_u32_e32 v14, 0x8c0, v0
	v_add_u32_e32 v16, 0xc00, v0
	v_add_u32_e32 v18, 0xc40, v0
	v_add_u32_e32 v20, 0xc80, v0
	v_add_u32_e32 v0, 0xcc0, v0
	v_ashrrev_i32_e32 v9, 31, v8
	v_ashrrev_i32_e32 v11, 31, v10
	v_ashrrev_i32_e32 v13, 31, v12
	v_ashrrev_i32_e32 v15, 31, v14
	v_ashrrev_i32_e32 v17, 31, v16
	v_ashrrev_i32_e32 v19, 31, v18
	v_ashrrev_i32_e32 v21, 31, v20
	v_ashrrev_i32_e32 v1, 31, v0
	s_and_b32 s2, s2, 31
	v_lshl_add_u64 v[8:9], v[8:9], 2, s[20:21]
	v_lshl_add_u64 v[10:11], v[10:11], 2, s[20:21]
	v_lshl_add_u64 v[12:13], v[12:13], 2, s[20:21]
	v_lshl_add_u64 v[14:15], v[14:15], 2, s[20:21]
	v_lshl_add_u64 v[16:17], v[16:17], 2, s[20:21]
	v_lshl_add_u64 v[18:19], v[18:19], 2, s[20:21]
	v_lshl_add_u64 v[20:21], v[20:21], 2, s[20:21]
	v_lshl_add_u64 v[0:1], v[0:1], 2, s[20:21]
	s_or_b32 s20, s66, s2
	s_ashr_i32 s21, s20, 31
	v_add_u32_e32 v28, 32, v54
	v_sub_u32_e32 v29, 31, v54
	s_lshl_b64 s[40:41], s[20:21], 4
	v_ashrrev_i32_e32 v47, 31, v46
	v_cndmask_b32_e64 v50, v29, v28, s[36:37]
	v_readlane_b32 s1, v254, 62
	s_lshl_b32 vcc_lo, s45, 1
	s_or_b32 s2, s40, s82
	s_lshl_b64 s[20:21], s[20:21], 15
	v_lshlrev_b64 v[112:113], 9, v[46:47]
	v_ashrrev_i32_e32 v51, 31, v50
	global_load_dword v8, v[8:9], off
	s_nop 0
	global_load_dword v9, v[10:11], off
	s_nop 0
	global_load_dword v10, v[12:13], off
	global_load_dword v11, v[14:15], off
	s_nop 0
	global_load_dword v12, v[16:17], off
	global_load_dword v13, v[18:19], off
	global_load_dword v14, v[20:21], off
	global_load_dword v15, v[0:1], off
	s_or_b32 s40, s2, vcc_lo
	v_lshl_add_u64 v[0:1], v[112:113], 0, s[20:21]
	v_readlane_b32 s0, v253, 5
	v_readlane_b32 s2, v253, 7
	v_lshlrev_b64 v[116:117], 9, v[50:51]
	v_lshlrev_b64 v[0:1], 1, v[0:1]
	v_readlane_b32 s1, v253, 6
	v_lshlrev_b32_e32 v18, 3, v44
	v_readlane_b32 s3, v253, 8
	v_lshl_add_u64 v[28:29], v[116:117], 0, s[20:21]
	s_lshl_b64 s[38:39], s[40:41], 13
	v_lshl_add_u64 v[16:17], s[0:1], 0, v[0:1]
	s_lshl_b32 s30, s45, 7
	v_and_b32_e32 v55, 56, v18
	v_lshl_add_u64 v[0:1], s[2:3], 0, v[0:1]
	v_readlane_b32 s4, v253, 9
	v_lshlrev_b64 v[36:37], 1, v[28:29]
	v_lshl_add_u64 v[16:17], v[16:17], 0, s[30:31]
	v_lshlrev_b32_e32 v48, 1, v55
	v_mov_b32_e32 v49, v2
	v_lshl_add_u64 v[0:1], v[0:1], 0, s[30:31]
	s_add_u32 s42, s4, s38
	v_readlane_b32 s4, v253, 10
	v_ashrrev_i32_e32 v45, 31, v44
	v_lshl_add_u64 v[28:29], s[0:1], 0, v[36:37]
	v_lshl_add_u64 v[16:17], v[16:17], 0, v[48:49]
	v_lshl_add_u64 v[0:1], v[0:1], 0, v[48:49]
	s_addc_u32 s43, s4, s39
	v_lshlrev_b64 v[114:115], 4, v[44:45]
	v_lshl_add_u64 v[28:29], v[28:29], 0, s[30:31]
	global_load_dwordx4 v[16:19], v[16:17], off
	s_nop 0
	global_load_dwordx4 v[20:23], v[0:1], off
	v_lshl_add_u64 v[0:1], s[42:43], 0, v[114:115]
	v_lshl_add_u64 v[32:33], v[28:29], 0, v[48:49]
	global_load_dwordx4 v[28:31], v[0:1], off
	s_nop 0
	global_load_dwordx4 v[32:35], v[32:33], off
	v_lshl_add_u64 v[0:1], s[2:3], 0, v[36:37]
	s_mov_b64 s[0:1], 0x1000
	v_lshl_add_u64 v[0:1], v[0:1], 0, s[30:31]
	v_lshl_add_u64 v[118:119], v[114:115], 0, s[0:1]
	v_and_b32_e32 v53, 63, v44
	v_lshl_add_u64 v[0:1], v[0:1], 0, v[48:49]
	v_lshl_add_u64 v[40:41], s[42:43], 0, v[118:119]
	global_load_dwordx4 v[36:39], v[0:1], off
	s_nop 0
	global_load_dwordx4 v[40:43], v[40:41], off
	v_lshl_or_b32 v0, s44, 8, v53
	v_ashrrev_i32_e32 v1, 31, v0
	v_readlane_b32 s0, v252, 26
	v_lshlrev_b64 v[120:121], 3, v[0:1]
	v_or_b32_e32 v58, 64, v0
	v_or_b32_e32 v60, 0x80, v0
	v_or_b32_e32 v0, 0xc0, v0
	v_readlane_b32 s1, v252, 27
	s_add_u32 s20, s0, s38
	v_ashrrev_i32_e32 v1, 31, v0
	s_addc_u32 s21, s1, s39
	v_ashrrev_i32_e32 v59, 31, v58
	v_ashrrev_i32_e32 v61, 31, v60
	v_lshlrev_b64 v[126:127], 3, v[0:1]
	v_lshl_add_u64 v[56:57], s[20:21], 0, v[120:121]
	v_lshlrev_b64 v[122:123], 3, v[58:59]
	v_lshlrev_b64 v[124:125], 3, v[60:61]
	v_lshl_add_u64 v[0:1], s[20:21], 0, v[126:127]
	v_lshl_add_u64 v[58:59], s[20:21], 0, v[122:123]
	v_lshl_add_u64 v[60:61], s[20:21], 0, v[124:125]
	global_load_dwordx2 v[72:73], v[56:57], off
	global_load_dwordx2 v[70:71], v[58:59], off
	global_load_dwordx2 v[68:69], v[60:61], off
	s_nop 0
	global_load_dwordx2 v[0:1], v[0:1], off
	s_mov_b32 s89, s57
	v_cmp_gt_i32_e64 s[38:39], 64, v44
	v_mov_b32_e32 v201, 0
	v_readlane_b32 s5, v250, 2
	v_readlane_b32 s6, v250, 3
	v_readlane_b32 s7, v250, 4
	v_readlane_b32 s8, v250, 5
	v_readlane_b32 s9, v250, 6
	v_readlane_b32 s10, v250, 7
	v_readlane_b32 s11, v250, 8
	v_readlane_b32 s12, v250, 9
	v_readlane_b32 s13, v250, 10
	v_readlane_b32 s14, v250, 11
	v_readlane_b32 s15, v250, 12
	s_and_saveexec_b64 s[42:43], s[38:39]
	s_cbranch_execz .LBB0_318
	s_lshl_b64 s[20:21], s[40:41], 8
	v_readlane_b32 s0, v253, 11
	v_readlane_b32 s1, v253, 12
	s_add_u32 s20, s0, s20
	s_addc_u32 s21, s1, s21
	v_lshl_add_u64 v[56:57], v[44:45], 2, s[20:21]
	global_load_dword v201, v[56:57], off

.LBB0_331:
	s_mov_b32 s57, s89
	s_setprio 0
	v_readlane_b32 s59, v255, 9
	s_barrier
